# combo5
# baseline (speedup 1.0000x reference)
.LBB0_938:
	s_or_b64 exec, exec, s[8:9]
	s_waitcnt vmcnt(0)
	v_readfirstlane_b32 s6, v2
	s_nop 1
	v_add3_u32 v0, s6, v0, 1
	v_readlane_b32 s6, v254, 33
	s_mul_i32 s6, s12, s6
	s_nop 0
	v_cmp_eq_u32_e32 vcc, s6, v0
	s_and_saveexec_b64 s[6:7], vcc
	s_cbranch_execz .LBB0_958
	s_mov_b64 s[8:9], exec
	v_mbcnt_lo_u32_b32 v0, s8, 0
	v_mbcnt_hi_u32_b32 v0, s9, v0
	v_cmp_eq_u32_e32 vcc, 0, v0
	s_and_saveexec_b64 s[10:11], vcc
	s_cbranch_execz .LBB0_944
	s_bcnt1_i32_b64 s8, s[8:9]
	v_mov_b32_e32 v0, s8
	v_readlane_b32 s8, v254, 40
	v_readlane_b32 s9, v254, 41
	s_nop 4
	global_atomic_add v1, v0, s[8:9]

.LBB0_958:
	s_or_b64 exec, exec, s[6:7]
	s_mov_b32 s8, 0x1000000
	v_readlane_b32 s9, v254, 37
	s_mul_i32 s9, s12, s9
	s_branch .LBB0_961

.LBB0_961:
	v_readlane_b32 s6, v254, 35
	v_readlane_b32 s7, v254, 36
	s_nop 4
	global_load_dword v0, v1, s[6:7] offset:2560 sc1
	s_mov_b64 s[6:7], -1
	s_waitcnt vmcnt(0)
	v_cmp_le_u32_e32 vcc, s9, v0
	s_cbranch_vccnz .LBB0_960
	s_cmp_lg_u32 s8, 0
	s_sleep 2
	s_cbranch_scc0 .LBB0_959
	v_readlane_b32 s6, v254, 35
	v_readlane_b32 s7, v254, 36
	s_nop 4
	global_load_dword v0, v1, s[6:7] offset:2560 sc1
	s_mov_b64 s[6:7], -1
	s_waitcnt vmcnt(0)
	v_cmp_gt_u32_e32 vcc, s9, v0
	s_cbranch_vccz .LBB0_960
	v_readlane_b32 s6, v254, 35
	v_readlane_b32 s7, v254, 36
	s_sleep 2
	s_nop 3
	global_load_dword v0, v1, s[6:7] offset:2560 sc1
	s_mov_b64 s[6:7], -1
	s_waitcnt vmcnt(0)
	v_cmp_gt_u32_e32 vcc, s9, v0
	s_cbranch_vccz .LBB0_960
	v_readlane_b32 s6, v254, 35
	v_readlane_b32 s7, v254, 36
	s_sleep 2
	s_nop 3
	global_load_dword v0, v1, s[6:7] offset:2560 sc1
	s_mov_b64 s[6:7], -1
	s_waitcnt vmcnt(0)
	v_cmp_gt_u32_e32 vcc, s9, v0
	s_cbranch_vccz .LBB0_960
	v_readlane_b32 s6, v254, 35
	v_readlane_b32 s7, v254, 36
	s_sleep 2
	s_nop 3
	global_load_dword v0, v1, s[6:7] offset:2560 sc1
	s_mov_b64 s[6:7], -1
	s_waitcnt vmcnt(0)
	v_cmp_gt_u32_e32 vcc, s9, v0
	s_cbranch_vccz .LBB0_960
	v_readlane_b32 s6, v254, 35
	v_readlane_b32 s7, v254, 36
	s_sleep 2
	s_nop 3
	global_load_dword v0, v1, s[6:7] offset:2560 sc1
	s_mov_b64 s[6:7], -1
	s_waitcnt vmcnt(0)
	v_cmp_gt_u32_e32 vcc, s9, v0
	s_cbranch_vccz .LBB0_960
	v_readlane_b32 s6, v254, 35
	v_readlane_b32 s7, v254, 36
	s_sleep 2
	s_nop 3
	global_load_dword v0, v1, s[6:7] offset:2560 sc1
	s_mov_b64 s[6:7], -1
	s_waitcnt vmcnt(0)
	v_cmp_gt_u32_e32 vcc, s9, v0
	s_cbranch_vccz .LBB0_960
	v_readlane_b32 s6, v254, 35
	v_readlane_b32 s7, v254, 36
	s_sleep 2
	s_nop 3
	global_load_dword v0, v1, s[6:7] offset:2560 sc1
	s_mov_b64 s[6:7], -1
	s_waitcnt vmcnt(0)
	v_cmp_gt_u32_e32 vcc, s9, v0
	s_cbranch_vccz .LBB0_960
	s_sleep 2
	s_add_i32 s8, s8, -8
	s_mov_b64 s[6:7], 0
	s_branch .LBB0_960
